# S item cross-wave sum: red[] reads use one base VGPR + immediate offsets instead of per-read v_readlane/s_nop/v_mov address re-materialisation
# speedup vs baseline: 1.0024x; 1.0024x over previous
.LBB0_789:
	s_or_b64 exec, exec, s[2:3]
	s_waitcnt lgkmcnt(0)
	s_barrier
	v_mov_b32_e32 v248, 0x16020
	ds_read_b128 v[6:9], v248 offset:32
	ds_read_b128 v[2:5], v248 offset:96
	ds_read_b128 v[14:17], v248 offset:160
	ds_read_b128 v[10:13], v248 offset:224
	ds_read_b128 v[22:25], v248 offset:288
	ds_read_b128 v[18:21], v248 offset:352
	ds_read_b128 v[30:33], v248 offset:416
	ds_read_b128 v[26:29], v248 offset:480
	ds_read_b128 v[38:41], v248 offset:48
	ds_read_b128 v[34:37], v248 offset:112
	ds_read_b128 v[46:49], v248 offset:176
	ds_read_b128 v[42:45], v248 offset:240
	ds_read_b128 v[54:57], v248 offset:304
	ds_read_b128 v[50:53], v248 offset:368
	ds_read_b128 v[62:65], v248 offset:432
	ds_read_b128 v[58:61], v248 offset:496
	s_and_saveexec_b64 s[34:35], s[42:43]
	s_cbranch_execz .LBB0_791
	v_lshlrev_b64 v[176:177], 2, v[172:173]
	v_lshl_add_u64 v[178:179], s[80:81], 0, v[176:177]
	v_lshl_add_u64 v[176:177], s[82:83], 0, v[176:177]
	global_load_dword v190, v[178:179], off
	global_load_dword v189, v[176:177], off
	s_mov_b32 s12, 0x3b2aaaab
	s_nop 0
	ds_read_b128 v[90:93], v248 offset:16
	s_nop 0
	ds_read_b128 v[94:97], v248 offset:80
	s_waitcnt lgkmcnt(0)
	v_mov_b32_e32 v176, v94
	ds_read_b128 v[98:101], v248 offset:144
	s_nop 0
	ds_read_b128 v[102:105], v248 offset:208
	s_nop 0
	ds_read_b128 v[106:109], v248 offset:272
	s_nop 0
	ds_read_b128 v[110:113], v248 offset:336
	s_nop 0
	ds_read_b128 v[114:117], v248 offset:400
	s_nop 0
	ds_read_b128 v[122:125], v248 offset:0
	ds_read_b128 v[118:121], v248 offset:464
	ds_read_b128 v[126:129], v248 offset:64
	s_waitcnt lgkmcnt(0)
	v_mov_b32_e32 v177, v126
	ds_read_b128 v[130:133], v248 offset:128
	v_mov_b32_e32 v126, v95
	ds_read_b128 v[134:137], v248 offset:192
	s_nop 0
	ds_read_b128 v[138:141], v248 offset:256
	s_nop 0
	ds_read_b128 v[142:145], v248 offset:320
	s_nop 0
	ds_read_b128 v[146:149], v248 offset:384
	s_nop 0
	v_readlane_b32 s2, v242, 40
	s_mulk_i32 s2, 0x300
	ds_read_b128 v[150:153], v248 offset:448
	v_add_u32_e32 v172, s2, v172
	v_ashrrev_i32_e32 v173, 31, v172
	v_lshl_add_u64 v[172:173], v[172:173], 2, s[84:85]
	global_load_dword v186, v[172:173], off
	global_load_dword v188, v[172:173], off offset:1536
	global_load_dword v187, v[172:173], off offset:3072
	v_mov_b32_e32 v172, v90
	v_mov_b32_e32 v173, v122
	v_pk_add_f32 v[172:173], v[172:173], 0 op_sel_hi:[1,0]
	s_movk_i32 s2, 0xd000
	v_pk_add_f32 v[172:173], v[172:173], v[176:177]
	v_mov_b32_e32 v176, v98
	s_waitcnt lgkmcnt(5)
	v_mov_b32_e32 v177, v130
	v_pk_add_f32 v[172:173], v[172:173], v[176:177]
	v_mov_b32_e32 v176, v102
	s_waitcnt lgkmcnt(4)
	v_mov_b32_e32 v177, v134
	v_pk_add_f32 v[172:173], v[172:173], v[176:177]
	v_mov_b32_e32 v176, v106
	s_waitcnt lgkmcnt(3)
	v_mov_b32_e32 v177, v138
	v_pk_add_f32 v[172:173], v[172:173], v[176:177]
	v_mov_b32_e32 v176, v110
	s_waitcnt lgkmcnt(2)
	v_mov_b32_e32 v177, v142
	v_pk_add_f32 v[172:173], v[172:173], v[176:177]
	v_mov_b32_e32 v176, v114
	s_waitcnt lgkmcnt(1)
	v_mov_b32_e32 v177, v146
	v_pk_add_f32 v[172:173], v[172:173], v[176:177]
	v_mov_b32_e32 v176, v118
	s_waitcnt lgkmcnt(0)
	v_mov_b32_e32 v177, v150
	v_pk_add_f32 v[172:173], v[172:173], v[176:177]
	v_lshlrev_b64 v[176:177], 1, v[164:165]
	v_pk_mul_f32 v[172:173], v[172:173], s[12:13] op_sel_hi:[1,0]
	v_mov_b32_e32 v122, v91
	v_fma_f32 v90, -v173, v173, v172
	v_max_f32_e32 v90, 0, v90
	v_add_f32_e32 v90, 0x358637bd, v90
	v_cmp_gt_f32_e32 vcc, s33, v90
	v_mul_f32_e32 v94, 0x4b800000, v90
	v_mov_b32_e32 v130, v99
	v_cndmask_b32_e32 v90, v90, v94, vcc
	v_rsq_f32_e32 v90, v90
	v_mov_b32_e32 v134, v103
	v_mov_b32_e32 v138, v107
	v_mov_b32_e32 v142, v111
	v_mul_f32_e32 v94, 0x45800000, v90
	v_cndmask_b32_e32 v90, v90, v94, vcc
	v_sub_f32_e32 v94, v174, v173
	v_mul_f32_e32 v90, v94, v90
	s_waitcnt vmcnt(3)
	v_fma_f32 v90, v190, v90, v189
	v_mul_f32_e32 v94, 0xbfb8aa3b, v90
	v_exp_f32_e32 v94, v94
	v_lshl_add_u64 v[172:173], s[30:31], 0, v[176:177]
	v_add_co_u32_e32 v178, vcc, s2, v172
	v_add_f32_e32 v94, 1.0, v94
	v_rcp_f32_e32 v94, v94
	v_addc_co_u32_e32 v179, vcc, -1, v173, vcc
	v_lshl_add_u64 v[176:177], s[10:11], 0, v[176:177]
	v_mul_f32_e32 v90, v90, v94
	v_mov_b32_e32 v146, v115
	v_mov_b32_e32 v150, v119
	s_movk_i32 s2, 0xe000
	s_waitcnt vmcnt(0)
	v_lshlrev_b32_e32 v94, 16, v192
	v_mul_f32_e32 v90, v90, v94
	v_bfe_u32 v94, v90, 16, 1
	v_add3_u32 v90, v90, v94, s15
	v_lshrrev_b32_e64 v245, 3, s7
	v_lshlrev_b32_e32 v245, 16, v245
	v_and_b32_e64 v246, s7, 7
	v_lshl_add_u32 v245, v246, 6, v245
	v_add_u32_e32 v245, 0x2000000, v245
	v_mov_b32_e32 v247, 0
	v_mov_b32_e32 v252, v0
	v_lshrrev_b32_e32 v246, 7, v252
	v_lshl_add_u32 v246, v246, 13, v245
	v_bfe_u32 v253, v252, 4, 3
	v_lshl_add_u32 v246, v253, 10, v246
	v_bfe_u32 v253, v252, 3, 1
	v_lshl_add_u32 v246, v253, 9, v246
	v_and_b32_e32 v253, 7, v252
	v_lshl_add_u32 v246, v253, 1, v246
	v_lshl_add_u64 v[236:237], s[62:63], 0, v[246:247]
	v_add_u32_e32 v252, 0x180, v0
	v_lshrrev_b32_e32 v246, 7, v252
	v_lshl_add_u32 v246, v246, 13, v245
	v_bfe_u32 v253, v252, 4, 3
	v_lshl_add_u32 v246, v253, 10, v246
	v_bfe_u32 v253, v252, 3, 1
	v_lshl_add_u32 v246, v253, 9, v246
	v_and_b32_e32 v253, 7, v252
	v_lshl_add_u32 v246, v253, 1, v246
	v_lshl_add_u64 v[238:239], s[62:63], 0, v[246:247]
	v_add_u32_e32 v252, 0x300, v0
	v_lshrrev_b32_e32 v246, 7, v252
	v_lshl_add_u32 v246, v246, 13, v245
	v_bfe_u32 v253, v252, 4, 3
	v_lshl_add_u32 v246, v253, 10, v246
	v_bfe_u32 v253, v252, 3, 1
	v_lshl_add_u32 v246, v253, 9, v246
	v_and_b32_e32 v253, 7, v252
	v_lshl_add_u32 v246, v253, 1, v246
	v_lshl_add_u64 v[240:241], s[62:63], 0, v[246:247]
	global_store_short_d16_hi v[236:237], v90, off
	v_mul_f32_e32 v90, v185, v188
	v_fmac_f32_e32 v90, v191, v186
	v_fmac_f32_e32 v90, v184, v187
	v_lshlrev_b32_e32 v94, 16, v193
	v_mul_f32_e32 v90, v90, v94
	v_bfe_u32 v94, v90, 16, 1
	v_add3_u32 v90, v90, v94, s15
	global_store_short_d16_hi v[238:239], v90, off
	v_pk_add_f32 v[90:91], v[122:123], 0 op_sel_hi:[1,0]
	s_nop 0
	v_pk_add_f32 v[90:91], v[90:91], v[126:127]
	s_nop 0
	v_pk_add_f32 v[90:91], v[90:91], v[130:131]
	s_nop 0
	v_pk_add_f32 v[90:91], v[90:91], v[134:135]
	s_nop 0
	v_pk_add_f32 v[90:91], v[90:91], v[138:139]
	s_nop 0
	v_pk_add_f32 v[90:91], v[90:91], v[142:143]
	s_nop 0
	v_pk_add_f32 v[90:91], v[90:91], v[146:147]
	s_nop 0
	v_pk_add_f32 v[90:91], v[90:91], v[150:151]
	s_nop 0
	v_pk_mul_f32 v[90:91], v[90:91], s[12:13] op_sel_hi:[1,0]
	s_nop 0
	v_fma_f32 v90, -v91, v91, v90
	v_max_f32_e32 v90, 0, v90
	v_add_f32_e32 v90, 0x358637bd, v90
	v_cmp_gt_f32_e32 vcc, s33, v90
	v_mul_f32_e32 v94, 0x4b800000, v90
	v_sub_f32_e32 v91, v175, v91
	v_cndmask_b32_e32 v90, v90, v94, vcc
	v_rsq_f32_e32 v90, v90
	s_nop 0
	v_mul_f32_e32 v94, 0x45800000, v90
	v_cndmask_b32_e32 v90, v90, v94, vcc
	v_mul_f32_e32 v90, v91, v90
	v_fma_f32 v90, v190, v90, v189
	v_mul_f32_e32 v91, 0xbfb8aa3b, v90
	v_exp_f32_e32 v91, v91
	s_nop 0
	v_add_f32_e32 v91, 1.0, v91
	v_rcp_f32_e32 v91, v91
	s_nop 0
	v_mul_f32_e32 v94, v90, v91
	v_add_co_u32_e32 v90, vcc, s2, v172
	s_movk_i32 s2, 0xf000
	s_nop 0
	v_addc_co_u32_e32 v91, vcc, -1, v173, vcc
	v_lshlrev_b32_e32 v95, 16, v194
	v_mul_f32_e32 v94, v94, v95
	v_bfe_u32 v95, v94, 16, 1
	v_add3_u32 v94, v94, v95, s15
	global_store_short_d16_hi v[236:237], v94, off offset:16
	v_mul_f32_e32 v94, v184, v188
	v_fmac_f32_e32 v94, v185, v186
	v_fmac_f32_e32 v94, v183, v187
	v_mov_b32_e32 v95, v128
	v_mov_b32_e32 v128, v97
	v_lshlrev_b32_e32 v90, 16, v195
	v_mul_f32_e32 v90, v94, v90
	v_bfe_u32 v91, v90, 16, 1
	v_add3_u32 v90, v90, v91, s15
	global_store_short_d16_hi v[238:239], v90, off offset:16
	v_mov_b32_e32 v90, v92
	v_mov_b32_e32 v91, v124
	v_pk_add_f32 v[90:91], v[90:91], 0 op_sel_hi:[1,0]
	v_mov_b32_e32 v94, v96
	v_pk_add_f32 v[90:91], v[90:91], v[94:95]
	v_mov_b32_e32 v94, v100
	v_mov_b32_e32 v95, v132
	v_pk_add_f32 v[90:91], v[90:91], v[94:95]
	v_mov_b32_e32 v94, v104
	v_mov_b32_e32 v95, v136
	v_pk_add_f32 v[90:91], v[90:91], v[94:95]
	v_mov_b32_e32 v94, v108
	v_mov_b32_e32 v95, v140
	v_pk_add_f32 v[90:91], v[90:91], v[94:95]
	v_mov_b32_e32 v94, v112
	v_mov_b32_e32 v95, v144
	v_pk_add_f32 v[90:91], v[90:91], v[94:95]
	v_mov_b32_e32 v94, v116
	v_mov_b32_e32 v95, v148
	v_pk_add_f32 v[90:91], v[90:91], v[94:95]
	v_mov_b32_e32 v94, v120
	v_mov_b32_e32 v95, v152
	v_pk_add_f32 v[90:91], v[90:91], v[94:95]
	v_mov_b32_e32 v124, v93
	v_pk_mul_f32 v[90:91], v[90:91], s[12:13] op_sel_hi:[1,0]
	v_mov_b32_e32 v132, v101
	v_fma_f32 v90, -v91, v91, v90
	v_max_f32_e32 v90, 0, v90
	v_add_f32_e32 v90, 0x358637bd, v90
	v_cmp_gt_f32_e32 vcc, s33, v90
	v_mul_f32_e32 v92, 0x4b800000, v90
	v_sub_f32_e32 v91, v170, v91
	v_cndmask_b32_e32 v90, v90, v92, vcc
	v_rsq_f32_e32 v90, v90
	v_mov_b32_e32 v136, v105
	v_mov_b32_e32 v140, v109
	v_mov_b32_e32 v144, v113
	v_mul_f32_e32 v92, 0x45800000, v90
	v_cndmask_b32_e32 v90, v90, v92, vcc
	v_mul_f32_e32 v90, v91, v90
	v_fma_f32 v90, v90, v190, v189
	v_mul_f32_e32 v91, 0xbfb8aa3b, v90
	v_exp_f32_e32 v91, v91
	v_add_co_u32_e32 v94, vcc, s2, v172
	s_movk_i32 s2, 0x1000
	v_add_f32_e32 v91, 1.0, v91
	v_rcp_f32_e32 v91, v91
	v_addc_co_u32_e32 v95, vcc, -1, v173, vcc
	v_mov_b32_e32 v148, v117
	v_mul_f32_e32 v90, v90, v91
	v_mov_b32_e32 v152, v121
	v_lshlrev_b32_e32 v91, 16, v196
	v_mul_f32_e32 v90, v90, v91
	v_bfe_u32 v91, v90, 16, 1
	v_add3_u32 v92, v90, v91, s15
	v_add_co_u32_e32 v90, vcc, s2, v176
	s_add_i32 s2, s4, s7
	s_nop 0
	v_addc_co_u32_e32 v91, vcc, 0, v177, vcc
	global_store_short_d16_hi v[236:237], v92, off offset:32
	v_mul_f32_e32 v92, v183, v188
	v_fmac_f32_e32 v92, v184, v186
	v_fmac_f32_e32 v92, v182, v187
	s_mul_hi_i32 s3, s2, 0xc00
	s_mulk_i32 s2, 0xc00
	s_add_u32 s2, s50, s2
	s_addc_u32 s3, s51, s3
	v_lshlrev_b32_e32 v94, 16, v197
	v_mul_f32_e32 v92, v92, v94
	v_bfe_u32 v94, v92, 16, 1
	v_add3_u32 v92, v92, v94, s15
	global_store_short_d16_hi v[238:239], v92, off offset:32
	v_pk_add_f32 v[92:93], v[124:125], 0 op_sel_hi:[1,0]
	s_nop 0
	v_pk_add_f32 v[92:93], v[92:93], v[128:129]
	s_nop 0
	v_pk_add_f32 v[92:93], v[92:93], v[132:133]
	s_nop 0
	v_pk_add_f32 v[92:93], v[92:93], v[136:137]
	s_nop 0
	v_pk_add_f32 v[92:93], v[92:93], v[140:141]
	s_nop 0
	v_pk_add_f32 v[92:93], v[92:93], v[144:145]
	s_nop 0
	v_pk_add_f32 v[92:93], v[92:93], v[148:149]
	s_nop 0
	v_pk_add_f32 v[92:93], v[92:93], v[152:153]
	s_nop 0
	v_pk_mul_f32 v[92:93], v[92:93], s[12:13] op_sel_hi:[1,0]
	s_nop 0
	v_fma_f32 v92, -v93, v93, v92
	v_max_f32_e32 v92, 0, v92
	v_add_f32_e32 v92, 0x358637bd, v92
	v_cmp_gt_f32_e32 vcc, s33, v92
	v_mul_f32_e32 v94, 0x4b800000, v92
	v_sub_f32_e32 v93, v171, v93
	v_cndmask_b32_e32 v92, v92, v94, vcc
	v_rsq_f32_e32 v92, v92
	s_nop 0
	v_mul_f32_e32 v94, 0x45800000, v92
	v_cndmask_b32_e32 v92, v92, v94, vcc
	v_mul_f32_e32 v92, v93, v92
	v_fmac_f32_e32 v189, v92, v190
	v_mul_f32_e32 v92, 0xbfb8aa3b, v189
	v_exp_f32_e32 v92, v92
	v_lshlrev_b32_e32 v93, 16, v198
	v_add_f32_e32 v92, 1.0, v92
	v_rcp_f32_e32 v92, v92
	s_nop 0
	v_mul_f32_e32 v92, v189, v92
	v_mul_f32_e32 v92, v92, v93
	v_bfe_u32 v93, v92, 16, 1
	v_add3_u32 v92, v92, v93, s15
	global_store_short_d16_hi v[236:237], v92, off offset:48
	v_mul_f32_e32 v92, v182, v188
	v_fmac_f32_e32 v92, v183, v186
	v_fmac_f32_e32 v92, v154, v187
	v_lshlrev_b32_e32 v93, 16, v199
	v_mul_f32_e32 v92, v92, v93
	v_bfe_u32 v93, v92, 16, 1
	v_add3_u32 v92, v92, v93, s15
	global_store_short_d16_hi v[238:239], v92, off offset:48
	v_lshl_add_u64 v[90:91], v[164:165], 2, s[2:3]
	v_add_co_u32_e32 v90, vcc, 0x4e00000, v90
	s_nop 1
	v_addc_co_u32_e32 v91, vcc, 0, v91, vcc
	global_store_dword v[90:91], v182, off
	global_store_dword v[90:91], v154, off offset:1536

.LBB0_859:
	s_or_b64 exec, exec, s[2:3]
	s_waitcnt lgkmcnt(0)
	s_barrier
	v_mov_b32_e32 v248, 0x16020
	ds_read_b128 v[6:9], v248 offset:32
	ds_read_b128 v[2:5], v248 offset:96
	ds_read_b128 v[14:17], v248 offset:160
	ds_read_b128 v[10:13], v248 offset:224
	ds_read_b128 v[22:25], v248 offset:288
	ds_read_b128 v[18:21], v248 offset:352
	ds_read_b128 v[30:33], v248 offset:416
	ds_read_b128 v[26:29], v248 offset:480
	ds_read_b128 v[38:41], v248 offset:48
	ds_read_b128 v[34:37], v248 offset:112
	ds_read_b128 v[46:49], v248 offset:176
	ds_read_b128 v[42:45], v248 offset:240
	ds_read_b128 v[54:57], v248 offset:304
	ds_read_b128 v[50:53], v248 offset:368
	ds_read_b128 v[62:65], v248 offset:432
	ds_read_b128 v[58:61], v248 offset:496
	s_and_saveexec_b64 s[34:35], s[38:39]
	s_cbranch_execz .LBB0_861
	v_lshlrev_b64 v[142:143], 2, v[138:139]
	v_lshl_add_u64 v[144:145], s[80:81], 0, v[142:143]
	v_lshl_add_u64 v[142:143], s[82:83], 0, v[142:143]
	global_load_dword v164, v[144:145], off
	global_load_dword v154, v[142:143], off
	s_mov_b32 s12, 0x3b2aaaab
	s_nop 0
	ds_read_b128 v[66:69], v248 offset:16
	s_nop 0
	ds_read_b128 v[70:73], v248 offset:80
	s_waitcnt lgkmcnt(0)
	v_mov_b32_e32 v142, v70
	ds_read_b128 v[74:77], v248 offset:144
	s_nop 0
	ds_read_b128 v[78:81], v248 offset:208
	s_nop 0
	ds_read_b128 v[82:85], v248 offset:272
	s_nop 0
	ds_read_b128 v[86:89], v248 offset:336
	s_nop 0
	ds_read_b128 v[90:93], v248 offset:400
	s_nop 0
	ds_read_b128 v[98:101], v248 offset:0
	ds_read_b128 v[94:97], v248 offset:464
	ds_read_b128 v[102:105], v248 offset:64
	s_waitcnt lgkmcnt(0)
	v_mov_b32_e32 v143, v102
	ds_read_b128 v[106:109], v248 offset:128
	v_mov_b32_e32 v102, v71
	ds_read_b128 v[110:113], v248 offset:192
	s_nop 0
	ds_read_b128 v[114:117], v248 offset:256
	s_nop 0
	ds_read_b128 v[118:121], v248 offset:320
	s_nop 0
	ds_read_b128 v[122:125], v248 offset:384
	s_nop 0
	v_readlane_b32 s2, v242, 40
	s_mulk_i32 s2, 0x300
	ds_read_b128 v[126:129], v248 offset:448
	v_add_u32_e32 v138, s2, v138
	v_ashrrev_i32_e32 v139, 31, v138
	v_lshl_add_u64 v[138:139], v[138:139], 2, s[84:85]
	global_load_dword v151, v[138:139], off
	global_load_dword v153, v[138:139], off offset:1536
	global_load_dword v152, v[138:139], off offset:3072
	v_mov_b32_e32 v138, v66
	v_mov_b32_e32 v139, v98
	v_pk_add_f32 v[138:139], v[138:139], 0 op_sel_hi:[1,0]
	s_movk_i32 s2, 0xd000
	v_pk_add_f32 v[138:139], v[138:139], v[142:143]
	v_mov_b32_e32 v142, v74
	s_waitcnt lgkmcnt(5)
	v_mov_b32_e32 v143, v106
	v_pk_add_f32 v[138:139], v[138:139], v[142:143]
	v_mov_b32_e32 v142, v78
	s_waitcnt lgkmcnt(4)
	v_mov_b32_e32 v143, v110
	v_pk_add_f32 v[138:139], v[138:139], v[142:143]
	v_mov_b32_e32 v142, v82
	s_waitcnt lgkmcnt(3)
	v_mov_b32_e32 v143, v114
	v_pk_add_f32 v[138:139], v[138:139], v[142:143]
	v_mov_b32_e32 v142, v86
	s_waitcnt lgkmcnt(2)
	v_mov_b32_e32 v143, v118
	v_pk_add_f32 v[138:139], v[138:139], v[142:143]
	v_mov_b32_e32 v142, v90
	s_waitcnt lgkmcnt(1)
	v_mov_b32_e32 v143, v122
	v_pk_add_f32 v[138:139], v[138:139], v[142:143]
	v_mov_b32_e32 v142, v94
	s_waitcnt lgkmcnt(0)
	v_mov_b32_e32 v143, v126
	v_pk_add_f32 v[138:139], v[138:139], v[142:143]
	v_lshlrev_b64 v[142:143], 1, v[130:131]
	v_pk_mul_f32 v[138:139], v[138:139], s[12:13] op_sel_hi:[1,0]
	v_mov_b32_e32 v98, v67
	v_fma_f32 v66, -v139, v139, v138
	v_max_f32_e32 v66, 0, v66
	v_add_f32_e32 v66, 0x358637bd, v66
	v_cmp_gt_f32_e32 vcc, s33, v66
	v_mul_f32_e32 v70, 0x4b800000, v66
	v_mov_b32_e32 v106, v75
	v_cndmask_b32_e32 v66, v66, v70, vcc
	v_rsq_f32_e32 v66, v66
	v_mov_b32_e32 v110, v79
	v_mov_b32_e32 v114, v83
	v_mov_b32_e32 v118, v87
	v_mul_f32_e32 v70, 0x45800000, v66
	v_cndmask_b32_e32 v66, v66, v70, vcc
	v_sub_f32_e32 v70, v140, v139
	v_mul_f32_e32 v66, v70, v66
	s_waitcnt vmcnt(3)
	v_fma_f32 v66, v164, v66, v154
	v_mul_f32_e32 v70, 0xbfb8aa3b, v66
	v_exp_f32_e32 v70, v70
	v_lshl_add_u64 v[138:139], s[30:31], 0, v[142:143]
	v_add_co_u32_e32 v144, vcc, s2, v138
	v_add_f32_e32 v70, 1.0, v70
	v_rcp_f32_e32 v70, v70
	v_addc_co_u32_e32 v145, vcc, -1, v139, vcc
	v_lshl_add_u64 v[142:143], s[10:11], 0, v[142:143]
	v_mul_f32_e32 v66, v66, v70
	v_mov_b32_e32 v122, v91
	v_mov_b32_e32 v126, v95
	s_movk_i32 s2, 0xe000
	s_waitcnt vmcnt(0)
	v_lshlrev_b32_e32 v70, 16, v192
	v_mul_f32_e32 v66, v66, v70
	v_bfe_u32 v70, v66, 16, 1
	v_add3_u32 v66, v66, v70, s15
	v_lshrrev_b32_e64 v245, 3, s7
	v_lshlrev_b32_e32 v245, 16, v245
	v_and_b32_e64 v246, s7, 7
	v_lshl_add_u32 v245, v246, 6, v245
	v_add_u32_e32 v245, 0x2000000, v245
	v_mov_b32_e32 v247, 0
	v_mov_b32_e32 v252, v0
	v_lshrrev_b32_e32 v246, 7, v252
	v_lshl_add_u32 v246, v246, 13, v245
	v_bfe_u32 v253, v252, 4, 3
	v_lshl_add_u32 v246, v253, 10, v246
	v_bfe_u32 v253, v252, 3, 1
	v_lshl_add_u32 v246, v253, 9, v246
	v_and_b32_e32 v253, 7, v252
	v_lshl_add_u32 v246, v253, 1, v246
	v_lshl_add_u64 v[236:237], s[62:63], 0, v[246:247]
	v_add_u32_e32 v252, 0x180, v0
	v_lshrrev_b32_e32 v246, 7, v252
	v_lshl_add_u32 v246, v246, 13, v245
	v_bfe_u32 v253, v252, 4, 3
	v_lshl_add_u32 v246, v253, 10, v246
	v_bfe_u32 v253, v252, 3, 1
	v_lshl_add_u32 v246, v253, 9, v246
	v_and_b32_e32 v253, 7, v252
	v_lshl_add_u32 v246, v253, 1, v246
	v_lshl_add_u64 v[238:239], s[62:63], 0, v[246:247]
	v_add_u32_e32 v252, 0x300, v0
	v_lshrrev_b32_e32 v246, 7, v252
	v_lshl_add_u32 v246, v246, 13, v245
	v_bfe_u32 v253, v252, 4, 3
	v_lshl_add_u32 v246, v253, 10, v246
	v_bfe_u32 v253, v252, 3, 1
	v_lshl_add_u32 v246, v253, 9, v246
	v_and_b32_e32 v253, 7, v252
	v_lshl_add_u32 v246, v253, 1, v246
	v_lshl_add_u64 v[240:241], s[62:63], 0, v[246:247]
	global_store_short_d16_hi v[236:237], v66, off
	v_mul_f32_e32 v66, v150, v153
	v_fmac_f32_e32 v66, v165, v151
	v_fmac_f32_e32 v66, v149, v152
	v_lshlrev_b32_e32 v70, 16, v193
	v_mul_f32_e32 v66, v66, v70
	v_bfe_u32 v70, v66, 16, 1
	v_add3_u32 v66, v66, v70, s15
	global_store_short_d16_hi v[238:239], v66, off
	v_pk_add_f32 v[66:67], v[98:99], 0 op_sel_hi:[1,0]
	s_nop 0
	v_pk_add_f32 v[66:67], v[66:67], v[102:103]
	s_nop 0
	v_pk_add_f32 v[66:67], v[66:67], v[106:107]
	s_nop 0
	v_pk_add_f32 v[66:67], v[66:67], v[110:111]
	s_nop 0
	v_pk_add_f32 v[66:67], v[66:67], v[114:115]
	s_nop 0
	v_pk_add_f32 v[66:67], v[66:67], v[118:119]
	s_nop 0
	v_pk_add_f32 v[66:67], v[66:67], v[122:123]
	s_nop 0
	v_pk_add_f32 v[66:67], v[66:67], v[126:127]
	s_nop 0
	v_pk_mul_f32 v[66:67], v[66:67], s[12:13] op_sel_hi:[1,0]
	s_nop 0
	v_fma_f32 v66, -v67, v67, v66
	v_max_f32_e32 v66, 0, v66
	v_add_f32_e32 v66, 0x358637bd, v66
	v_cmp_gt_f32_e32 vcc, s33, v66
	v_mul_f32_e32 v70, 0x4b800000, v66
	v_sub_f32_e32 v67, v141, v67
	v_cndmask_b32_e32 v66, v66, v70, vcc
	v_rsq_f32_e32 v66, v66
	s_nop 0
	v_mul_f32_e32 v70, 0x45800000, v66
	v_cndmask_b32_e32 v66, v66, v70, vcc
	v_mul_f32_e32 v66, v67, v66
	v_fma_f32 v66, v164, v66, v154
	v_mul_f32_e32 v67, 0xbfb8aa3b, v66
	v_exp_f32_e32 v67, v67
	s_nop 0
	v_add_f32_e32 v67, 1.0, v67
	v_rcp_f32_e32 v67, v67
	s_nop 0
	v_mul_f32_e32 v70, v66, v67
	v_add_co_u32_e32 v66, vcc, s2, v138
	s_movk_i32 s2, 0xf000
	s_nop 0
	v_addc_co_u32_e32 v67, vcc, -1, v139, vcc
	v_lshlrev_b32_e32 v71, 16, v194
	v_mul_f32_e32 v70, v70, v71
	v_bfe_u32 v71, v70, 16, 1
	v_add3_u32 v70, v70, v71, s15
	global_store_short_d16_hi v[236:237], v70, off offset:16
	v_mul_f32_e32 v70, v149, v153
	v_fmac_f32_e32 v70, v150, v151
	v_fmac_f32_e32 v70, v148, v152
	v_mov_b32_e32 v71, v104
	v_mov_b32_e32 v104, v73
	v_lshlrev_b32_e32 v66, 16, v195
	v_mul_f32_e32 v66, v70, v66
	v_bfe_u32 v67, v66, 16, 1
	v_add3_u32 v66, v66, v67, s15
	global_store_short_d16_hi v[238:239], v66, off offset:16
	v_mov_b32_e32 v66, v68
	v_mov_b32_e32 v67, v100
	v_pk_add_f32 v[66:67], v[66:67], 0 op_sel_hi:[1,0]
	v_mov_b32_e32 v70, v72
	v_pk_add_f32 v[66:67], v[66:67], v[70:71]
	v_mov_b32_e32 v70, v76
	v_mov_b32_e32 v71, v108
	v_pk_add_f32 v[66:67], v[66:67], v[70:71]
	v_mov_b32_e32 v70, v80
	v_mov_b32_e32 v71, v112
	v_pk_add_f32 v[66:67], v[66:67], v[70:71]
	v_mov_b32_e32 v70, v84
	v_mov_b32_e32 v71, v116
	v_pk_add_f32 v[66:67], v[66:67], v[70:71]
	v_mov_b32_e32 v70, v88
	v_mov_b32_e32 v71, v120
	v_pk_add_f32 v[66:67], v[66:67], v[70:71]
	v_mov_b32_e32 v70, v92
	v_mov_b32_e32 v71, v124
	v_pk_add_f32 v[66:67], v[66:67], v[70:71]
	v_mov_b32_e32 v70, v96
	v_mov_b32_e32 v71, v128
	v_pk_add_f32 v[66:67], v[66:67], v[70:71]
	v_mov_b32_e32 v100, v69
	v_pk_mul_f32 v[66:67], v[66:67], s[12:13] op_sel_hi:[1,0]
	v_mov_b32_e32 v108, v77
	v_fma_f32 v66, -v67, v67, v66
	v_max_f32_e32 v66, 0, v66
	v_add_f32_e32 v66, 0x358637bd, v66
	v_cmp_gt_f32_e32 vcc, s33, v66
	v_mul_f32_e32 v68, 0x4b800000, v66
	v_sub_f32_e32 v67, v136, v67
	v_cndmask_b32_e32 v66, v66, v68, vcc
	v_rsq_f32_e32 v66, v66
	v_mov_b32_e32 v112, v81
	v_mov_b32_e32 v116, v85
	v_mov_b32_e32 v120, v89
	v_mul_f32_e32 v68, 0x45800000, v66
	v_cndmask_b32_e32 v66, v66, v68, vcc
	v_mul_f32_e32 v66, v67, v66
	v_fma_f32 v66, v66, v164, v154
	v_mul_f32_e32 v67, 0xbfb8aa3b, v66
	v_exp_f32_e32 v67, v67
	v_add_co_u32_e32 v70, vcc, s2, v138
	s_movk_i32 s2, 0x1000
	v_add_f32_e32 v67, 1.0, v67
	v_rcp_f32_e32 v67, v67
	v_addc_co_u32_e32 v71, vcc, -1, v139, vcc
	v_mov_b32_e32 v124, v93
	v_mul_f32_e32 v66, v66, v67
	v_mov_b32_e32 v128, v97
	v_lshlrev_b32_e32 v67, 16, v196
	v_mul_f32_e32 v66, v66, v67
	v_bfe_u32 v67, v66, 16, 1
	v_add3_u32 v68, v66, v67, s15
	v_add_co_u32_e32 v66, vcc, s2, v142
	s_add_i32 s2, s4, s7
	s_nop 0
	v_addc_co_u32_e32 v67, vcc, 0, v143, vcc
	global_store_short_d16_hi v[236:237], v68, off offset:32
	v_mul_f32_e32 v68, v148, v153
	v_fmac_f32_e32 v68, v149, v151
	v_fmac_f32_e32 v68, v147, v152
	s_mul_hi_i32 s3, s2, 0xc00
	s_mulk_i32 s2, 0xc00
	s_add_u32 s2, s50, s2
	s_addc_u32 s3, s51, s3
	v_lshlrev_b32_e32 v70, 16, v197
	v_mul_f32_e32 v68, v68, v70
	v_bfe_u32 v70, v68, 16, 1
	v_add3_u32 v68, v68, v70, s15
	global_store_short_d16_hi v[238:239], v68, off offset:32
	v_pk_add_f32 v[68:69], v[100:101], 0 op_sel_hi:[1,0]
	s_nop 0
	v_pk_add_f32 v[68:69], v[68:69], v[104:105]
	s_nop 0
	v_pk_add_f32 v[68:69], v[68:69], v[108:109]
	s_nop 0
	v_pk_add_f32 v[68:69], v[68:69], v[112:113]
	s_nop 0
	v_pk_add_f32 v[68:69], v[68:69], v[116:117]
	s_nop 0
	v_pk_add_f32 v[68:69], v[68:69], v[120:121]
	s_nop 0
	v_pk_add_f32 v[68:69], v[68:69], v[124:125]
	s_nop 0
	v_pk_add_f32 v[68:69], v[68:69], v[128:129]
	s_nop 0
	v_pk_mul_f32 v[68:69], v[68:69], s[12:13] op_sel_hi:[1,0]
	s_nop 0
	v_fma_f32 v68, -v69, v69, v68
	v_max_f32_e32 v68, 0, v68
	v_add_f32_e32 v68, 0x358637bd, v68
	v_cmp_gt_f32_e32 vcc, s33, v68
	v_mul_f32_e32 v70, 0x4b800000, v68
	v_sub_f32_e32 v69, v137, v69
	v_cndmask_b32_e32 v68, v68, v70, vcc
	v_rsq_f32_e32 v68, v68
	s_nop 0
	v_mul_f32_e32 v70, 0x45800000, v68
	v_cndmask_b32_e32 v68, v68, v70, vcc
	v_mul_f32_e32 v68, v69, v68
	v_fmac_f32_e32 v154, v68, v164
	v_mul_f32_e32 v68, 0xbfb8aa3b, v154
	v_exp_f32_e32 v68, v68
	v_lshlrev_b32_e32 v69, 16, v198
	v_add_f32_e32 v68, 1.0, v68
	v_rcp_f32_e32 v68, v68
	s_nop 0
	v_mul_f32_e32 v68, v154, v68
	v_mul_f32_e32 v68, v68, v69
	v_bfe_u32 v69, v68, 16, 1
	v_add3_u32 v68, v68, v69, s15
	global_store_short_d16_hi v[236:237], v68, off offset:48
	v_mul_f32_e32 v68, v147, v153
	v_fmac_f32_e32 v68, v148, v151
	v_fmac_f32_e32 v68, v146, v152
	v_lshlrev_b32_e32 v69, 16, v199
	v_mul_f32_e32 v68, v68, v69
	v_bfe_u32 v69, v68, 16, 1
	v_add3_u32 v68, v68, v69, s15
	global_store_short_d16_hi v[238:239], v68, off offset:48
	v_lshl_add_u64 v[66:67], v[130:131], 2, s[2:3]
	v_add_co_u32_e32 v66, vcc, 0x4e00000, v66
	s_nop 1
	v_addc_co_u32_e32 v67, vcc, 0, v67, vcc
	global_store_dword v[66:67], v147, off
	global_store_dword v[66:67], v146, off offset:1536
